# P1 gate pre-activation task: loads of a half tile issued back to back with counted waits instead of vmcnt(0) before each MFMA (on top of v68)
# speedup vs baseline: 1.0043x; 1.0043x over previous
; __device__ __forceinline__ f32x4 mfma16(bf16x8 a, bf16x8 b, f32x4 c) { return __builtin_amdgcn_mfma_f32_16x16x32_bf16(a, b, c, 0, 0, 0); }
; __device__ __forceinline__ void gate_tile(const Params& P, int tile, int lane) {
;     const int l15 = lane & 15, q4 = lane >> 4;
;     const bf16* ap = (const bf16*)(P.ws + WS_XN) + (size_t)(16 * tile + l15) * 1024 + 8 * q4;
;     const bf16* bp = (const bf16*)(P.ws + WS_WAB) + (size_t)l15 * 1024 + 8 * q4;
;     f32x4 acc = {0.f, 0.f, 0.f, 0.f};
; #pragma unroll 16
;     for (int ks = 0; ks < 32; ++ks) acc = mfma16(*(const bf16x8*)(ap + 32 * ks), *(const bf16x8*)(bp + 32 * ks), acc);
;     float* Gd = (float*)(P.ws + WS_G); float* Bd = (float*)(P.ws + WS_BETA);
;     const int c = l15;
;     const float al = (c < 8) ? -expf(P.a_log[c]) : 0.f, db = (c < 8) ? P.dt_bias[c] : 0.f;
; #pragma unroll
;     for (int r = 0; r < 4; ++r) { const size_t mrow = (size_t)16 * tile + 4 * q4 + r; const float v = acc[r];
;         if (c < 8) { const float xx = v + db; const float sp = xx > 20.f ? xx : log1pf(expf(xx)); Gd[mrow * 8 + c] = al * sp; }
.LBB0_148:
	v_lshl_add_u64 v[24:25], v[22:23], 0, s[52:53]
	s_waitcnt vmcnt(0)
	v_add_co_u32_e32 v26, vcc, 0x23900000, v24
	s_nop 1
	v_addc_co_u32_e32 v27, vcc, 0, v25, vcc
	v_lshl_add_u64 v[24:25], v[20:21], 0, s[52:53]
	v_add_co_u32_e32 v24, vcc, 0xdc0000, v24
	s_add_u32 s52, s52, 0x400
	s_nop 0
	v_addc_co_u32_e32 v25, vcc, 0, v25, vcc
	s_addc_u32 s53, s53, 0
	s_cmpk_eq_i32 s52, 0x800
	global_load_dwordx4 v[28:31], v[24:25], off
	global_load_dwordx4 v[32:35], v[24:25], off offset:64
	global_load_dwordx4 v[36:39], v[24:25], off offset:128
	global_load_dwordx4 v[44:47], v[24:25], off offset:192
	global_load_dwordx4 v[48:51], v[24:25], off offset:256
	global_load_dwordx4 v[52:55], v[24:25], off offset:320
	global_load_dwordx4 v[56:59], v[24:25], off offset:384
	global_load_dwordx4 v[60:63], v[24:25], off offset:448
	global_load_dwordx4 v[66:69], v[26:27], off
	global_load_dwordx4 v[70:73], v[26:27], off offset:64
	global_load_dwordx4 v[74:77], v[26:27], off offset:128
	global_load_dwordx4 v[78:81], v[26:27], off offset:192
	global_load_dwordx4 v[82:85], v[26:27], off offset:256
	global_load_dwordx4 v[86:89], v[26:27], off offset:320
	global_load_dwordx4 v[90:93], v[26:27], off offset:384
	global_load_dwordx4 v[94:97], v[26:27], off offset:448
	global_load_dwordx4 v[98:101], v[26:27], off offset:512
	global_load_dwordx4 v[102:105], v[26:27], off offset:576
	global_load_dwordx4 v[106:109], v[26:27], off offset:640
	global_load_dwordx4 v[110:113], v[26:27], off offset:704
	global_load_dwordx4 v[114:117], v[26:27], off offset:768
	global_load_dwordx4 v[118:121], v[26:27], off offset:832
	global_load_dwordx4 v[122:125], v[26:27], off offset:896
	global_load_dwordx4 v[126:129], v[26:27], off offset:960
	s_waitcnt vmcnt(15)
	v_mfma_f32_16x16x32_bf16 v[2:5], v[66:69], v[28:31], v[2:5]
	global_load_dwordx4 v[28:31], v[24:25], off offset:512
	s_waitcnt vmcnt(15)
	v_mfma_f32_16x16x32_bf16 v[2:5], v[70:73], v[32:35], v[2:5]
	global_load_dwordx4 v[32:35], v[24:25], off offset:576
	s_waitcnt vmcnt(15)
	v_mfma_f32_16x16x32_bf16 v[2:5], v[74:77], v[36:39], v[2:5]
	global_load_dwordx4 v[36:39], v[24:25], off offset:640
	s_waitcnt vmcnt(15)
	v_mfma_f32_16x16x32_bf16 v[2:5], v[78:81], v[44:47], v[2:5]
	global_load_dwordx4 v[44:47], v[24:25], off offset:704
	s_waitcnt vmcnt(15)
	v_mfma_f32_16x16x32_bf16 v[2:5], v[82:85], v[48:51], v[2:5]
	global_load_dwordx4 v[48:51], v[24:25], off offset:768
	s_waitcnt vmcnt(15)
	v_mfma_f32_16x16x32_bf16 v[2:5], v[86:89], v[52:55], v[2:5]
	global_load_dwordx4 v[52:55], v[24:25], off offset:832
	s_waitcnt vmcnt(15)
	v_mfma_f32_16x16x32_bf16 v[2:5], v[90:93], v[56:59], v[2:5]
	global_load_dwordx4 v[56:59], v[24:25], off offset:896
	s_waitcnt vmcnt(15)
	v_mfma_f32_16x16x32_bf16 v[2:5], v[94:97], v[60:63], v[2:5]
	global_load_dwordx4 v[60:63], v[24:25], off offset:960
	s_waitcnt vmcnt(7)
	v_mfma_f32_16x16x32_bf16 v[2:5], v[98:101], v[28:31], v[2:5]
	s_waitcnt vmcnt(6)
	v_mfma_f32_16x16x32_bf16 v[2:5], v[102:105], v[32:35], v[2:5]
	s_waitcnt vmcnt(5)
	v_mfma_f32_16x16x32_bf16 v[2:5], v[106:109], v[36:39], v[2:5]
	s_waitcnt vmcnt(4)
	v_mfma_f32_16x16x32_bf16 v[2:5], v[110:113], v[44:47], v[2:5]
	s_waitcnt vmcnt(3)
	v_mfma_f32_16x16x32_bf16 v[2:5], v[114:117], v[48:51], v[2:5]
	s_waitcnt vmcnt(2)
	v_mfma_f32_16x16x32_bf16 v[2:5], v[118:121], v[52:55], v[2:5]
	s_waitcnt vmcnt(1)
	v_mfma_f32_16x16x32_bf16 v[2:5], v[122:125], v[56:59], v[2:5]
	s_waitcnt vmcnt(0)
	v_mfma_f32_16x16x32_bf16 v[2:5], v[126:129], v[60:63], v[2:5]
	s_cbranch_scc0 .LBB0_148
	v_mov_b32_e32 v26, 0
	v_mov_b32_e32 v19, 0
	s_and_saveexec_b64 s[52:53], s[0:1]
	s_cbranch_execz .LBB0_151
	global_load_dword v19, v[6:7], off
	s_waitcnt vmcnt(0)
	v_mul_f32_e32 v22, 0x3fb8aa3b, v19
	v_rndne_f32_e32 v23, v22
	v_fma_f32 v24, v19, s40, -v22
	v_sub_f32_e32 v22, v22, v23
	v_fmac_f32_e32 v24, 0x32a5705f, v19
	v_add_f32_e32 v22, v22, v24
	v_cvt_i32_f32_e32 v23, v23
	v_exp_f32_e32 v22, v22
	v_cmp_ngt_f32_e32 vcc, s97, v19
	v_ldexp_f32 v22, v22, v23
	s_nop 0
	v_cndmask_b32_e32 v22, 0, v22, vcc
	v_cmp_nlt_f32_e32 vcc, s35, v19
	s_nop 1
	v_cndmask_b32_e32 v19, v154, v22, vcc
	v_xor_b32_e32 v19, 0x80000000, v19
